# g2 step: state-update LDS reads issued together right after the barrier; attention sample items moved to the lightly loaded blocks
# speedup vs baseline: 1.0076x; 1.0044x over previous
.LBB0_135:
	ds_read_b128 v[72:75], v120
	ds_read_b128 v[76:79], v120 offset:64
	ds_read_b128 v[148:151], v121
	ds_read_b128 v[152:155], v121 offset:64
	ds_read_b128 v[80:83], v120 offset:128
	ds_read_b128 v[156:159], v120 offset:192
	ds_read_b128 v[160:163], v121 offset:128
	ds_read_b128 v[164:167], v121 offset:192
	ds_read_b64 v[168:169], v122 offset:62464
	s_setprio 1
	s_waitcnt lgkmcnt(6)
	v_mfma_f32_16x16x32_bf16 v[72:75], v[72:75], v[148:151], 0
	s_waitcnt lgkmcnt(5)
	v_mfma_f32_16x16x32_bf16 v[72:75], v[76:79], v[152:155], v[72:75]
	s_waitcnt lgkmcnt(0)
	v_lshlrev_b32_e32 v76, 16, v168
	v_and_b32_e32 v77, 0xffff0000, v168
	v_lshlrev_b32_e32 v78, 16, v169
	v_mfma_f32_16x16x32_bf16 v[72:75], v[80:83], v[160:163], v[72:75]
	v_and_b32_e32 v79, 0xffff0000, v169
	v_mfma_f32_16x16x32_bf16 v[72:75], v[156:159], v[164:167], v[72:75]
	s_nop 7
	v_pk_add_f32 v[72:73], v[76:77], v[72:73] neg_lo:[0,1] neg_hi:[0,1]
	v_pk_add_f32 v[74:75], v[78:79], v[74:75] neg_lo:[0,1] neg_hi:[0,1]
	v_cvt_pk_bf16_f32 v72, v72, v73
	v_cvt_pk_bf16_f32 v73, v74, v75
	ds_write_b64 v124, v[72:73]
	ds_read_b128 v[72:75], v120 offset:17408
	ds_read_b128 v[156:159], v120 offset:17472
	ds_read_b128 v[168:171], v120 offset:17536
	ds_read_b128 v[172:175], v120 offset:17600
	ds_read_b128 v[190:193], v125 offset:53248
	ds_read_b128 v[194:197], v125 offset:53312
	ds_read_b128 v[80:83], v126 offset:34816
	ds_read_b128 v[76:79], v126 offset:34880
	s_setprio 0
	s_waitcnt lgkmcnt(0)
	s_barrier
	s_setprio 1
	s_waitcnt lgkmcnt(7)
	v_mfma_f32_16x16x32_bf16 v[72:75], v[72:75], v[148:151], 0
	v_add_u32_e32 v149, v123, v119
	s_waitcnt lgkmcnt(6)
	v_mfma_f32_16x16x32_bf16 v[72:75], v[156:159], v[152:155], v[72:75]
	ds_read_b128 v[150:153], v149
	ds_read_b128 v[154:157], v149 offset:64
	ds_read_b128 v[216:219], v147
	ds_read_b128 v[220:223], v147 offset:64
	ds_read_b128 v[224:227], v147 offset:2304
	ds_read_b128 v[228:231], v147 offset:2368
	s_waitcnt lgkmcnt(7)
	v_mfma_f32_16x16x32_bf16 v[72:75], v[168:171], v[160:163], v[72:75]
	s_waitcnt lgkmcnt(6)
	v_mfma_f32_16x16x32_bf16 v[72:75], v[172:175], v[164:167], v[72:75]
	s_waitcnt lgkmcnt(5)
	v_mfma_f32_16x16x32_bf16 v[72:75], v[190:193], v[150:153], v[72:75]
	s_waitcnt lgkmcnt(4)
	v_mfma_f32_16x16x32_bf16 v[72:75], v[194:197], v[154:157], v[72:75]
	s_and_saveexec_b64 s[24:25], s[6:7]
	s_cbranch_execz .LBB0_139
	s_nop 5
	v_cvt_pk_bf16_f32 v72, v72, s0
	global_store_short v[110:111], v72, off offset:-4096
	s_or_b64 exec, exec, s[24:25]
	s_and_saveexec_b64 s[24:25], s[8:9]
	s_cbranch_execnz .LBB0_140

.LBB0_143:
	s_or_b64 exec, exec, s[24:25]
	s_nop 0
	v_pk_mul_f32 v[26:27], v[114:115], v[26:27] op_sel_hi:[0,1]
	v_pk_mul_f32 v[24:25], v[114:115], v[24:25] op_sel_hi:[0,1]
	s_waitcnt lgkmcnt(3)
	s_nop 0
	v_mfma_f32_16x16x32_bf16 v[24:27], v[80:83], v[216:219], v[24:27]
	s_nop 0
	s_waitcnt lgkmcnt(2)
	v_mfma_f32_16x16x32_bf16 v[72:75], v[76:79], v[220:223], v[24:27]
	s_nop 4
	v_mul_f32_e64 v26, v114, v38
	v_mul_f32_e64 v27, v114, v39
	s_nop 0
	v_cvt_pk_bf16_f32 v24, v72, v73
	v_cvt_pk_bf16_f32 v25, v74, v75
	ds_write_b64 v145, v[24:25]
	v_pk_mul_f32 v[24:25], v[114:115], v[36:37] op_sel_hi:[0,1]
	s_nop 0
	s_waitcnt lgkmcnt(2)
	v_mfma_f32_16x16x32_bf16 v[24:27], v[80:83], v[224:227], v[24:27]
	s_nop 0
	s_waitcnt lgkmcnt(1)
	v_mfma_f32_16x16x32_bf16 v[76:79], v[76:79], v[228:231], v[24:27]
	s_nop 7
	v_cvt_pk_bf16_f32 v24, v76, v77
	v_cvt_pk_bf16_f32 v25, v78, v79
	ds_write_b64 v145, v[24:25] offset:4352
	s_setprio 0
	s_waitcnt vmcnt(16)
	ds_write_b128 v127, v[0:3]
	s_waitcnt vmcnt(15)
	ds_write_b128 v128, v[4:7]
	s_waitcnt vmcnt(14)
	ds_write_b128 v129, v[8:11]
	s_waitcnt vmcnt(13)
	ds_write_b128 v130, v[12:15]
	s_waitcnt vmcnt(12)
	ds_write_b128 v131, v[16:19]
	s_waitcnt vmcnt(11)
	ds_write_b128 v132, v[20:23]
	s_waitcnt vmcnt(10)
	ds_write_b128 v133, v[28:31]
	s_and_saveexec_b64 s[24:25], s[4:5]
	s_cbranch_execz .LBB0_145
	s_waitcnt vmcnt(9)
	ds_write_b128 v134, v[32:35]
.LBB0_145:
	s_or_b64 exec, exec, s[24:25]
	s_waitcnt lgkmcnt(0)
	s_barrier
	s_add_i32 s24, s45, 1
	s_cmp_ge_u32 s24, s43
	s_cbranch_scc1 .LBB0_133
	s_add_i32 s24, s45, 3
	s_min_u32 s24, s24, s44
	s_add_i32 s24, s24, s42
	s_mul_hi_u32 s25, s24, 0x12100
	s_mul_i32 s24, s24, 0x12100
	s_add_u32 s24, s37, s24
	s_addc_u32 s25, s39, s25
	s_add_u32 s26, s24, 0x8000
	s_addc_u32 s27, s25, 0
	s_add_u32 s46, s24, 0xc000
	v_mov_b32_e32 v99, v137
	v_lshl_add_u64 v[22:23], s[24:25], 0, v[106:107]
	s_addc_u32 s47, s25, 0
	v_lshl_add_u64 v[22:23], v[22:23], 0, v[98:99]
	v_lshl_add_u64 v[0:1], s[24:25], 0, v[102:103]
	v_lshl_add_u64 v[4:5], s[24:25], 0, v[104:105]
	v_lshl_add_u64 v[6:7], s[26:27], 0, v[102:103]
	v_lshl_add_u64 v[12:13], s[26:27], 0, v[104:105]
	v_lshl_add_u64 v[14:15], s[46:47], 0, v[106:107]
	v_lshl_add_u64 v[20:21], v[84:85], 1, s[46:47]
	v_add_co_u32_e32 v24, vcc, s97, v22
	v_lshl_add_u64 v[0:1], v[0:1], 0, v[136:137]
	v_lshl_add_u64 v[4:5], v[4:5], 0, v[136:137]
	v_lshl_add_u64 v[8:9], v[6:7], 0, v[136:137]
	v_lshl_add_u64 v[12:13], v[12:13], 0, v[136:137]
	v_lshl_add_u64 v[16:17], v[14:15], 0, v[98:99]
	v_lshl_add_u64 v[20:21], v[20:21], 0, v[98:99]
	v_addc_co_u32_e32 v25, vcc, 0, v23, vcc
	v_mov_b32_e32 v109, v137
	global_load_dword v148, v206, s[24:25]
	s_nop 0
	global_load_dwordx4 v[0:3], v[0:1], off
	s_nop 0
	global_load_dwordx4 v[4:7], v[4:5], off
	s_nop 0
	global_load_dwordx4 v[8:11], v[8:9], off
	s_nop 0
	global_load_dwordx4 v[12:15], v[12:13], off
	s_nop 0
	global_load_dwordx4 v[16:19], v[16:17], off
	s_nop 0
	global_load_dwordx4 v[20:23], v[20:21], off
	s_nop 0
	global_load_dwordx4 v[28:31], v[24:25], off
	v_lshl_add_u64 v[24:25], s[24:25], 0, v[108:109]
	v_lshl_add_u64 v[24:25], v[24:25], 0, v[98:99]
	v_add_co_u32_e32 v24, vcc, s93, v24
	s_nop 1
	v_addc_co_u32_e32 v25, vcc, 0, v25, vcc
	global_load_dwordx4 v[32:35], v[24:25], off
	ds_read_b128 v[24:27], v135
	ds_read_b128 v[36:39], v135 offset:64
	ds_read_b128 v[150:153], v138
	ds_read_b128 v[154:157], v138 offset:64
	ds_read_b128 v[80:83], v135 offset:128
	ds_read_b128 v[158:161], v135 offset:192
	ds_read_b128 v[162:165], v138 offset:128
	ds_read_b128 v[166:169], v138 offset:192
	ds_read_b64 v[170:171], v139
	s_setprio 1
	s_waitcnt lgkmcnt(6)
	v_mfma_f32_16x16x32_bf16 v[24:27], v[24:27], v[150:153], 0
	s_waitcnt lgkmcnt(5)
	v_mfma_f32_16x16x32_bf16 v[24:27], v[36:39], v[154:157], v[24:27]
	s_waitcnt lgkmcnt(0)
	v_lshlrev_b32_e32 v36, 16, v170
	v_and_b32_e32 v37, 0xffff0000, v170
	v_lshlrev_b32_e32 v38, 16, v171
	v_mfma_f32_16x16x32_bf16 v[24:27], v[80:83], v[162:165], v[24:27]
	v_and_b32_e32 v39, 0xffff0000, v171
	v_mfma_f32_16x16x32_bf16 v[24:27], v[158:161], v[166:169], v[24:27]
	s_nop 7
	v_pk_add_f32 v[24:25], v[36:37], v[24:25] neg_lo:[0,1] neg_hi:[0,1]
	v_pk_add_f32 v[26:27], v[38:39], v[26:27] neg_lo:[0,1] neg_hi:[0,1]
	v_cvt_pk_bf16_f32 v24, v24, v25
	v_cvt_pk_bf16_f32 v25, v26, v27
	ds_write_b64 v124, v[24:25]
	ds_read_b128 v[24:27], v146
	ds_read_b128 v[158:161], v146 offset:64
	ds_read_b128 v[170:173], v146 offset:128
	ds_read_b128 v[174:177], v146 offset:192
	ds_read_b128 v[190:193], v140
	ds_read_b128 v[194:197], v140 offset:64
	ds_read_b128 v[80:83], v141
	ds_read_b128 v[36:39], v141 offset:64
	s_setprio 0
	s_waitcnt lgkmcnt(0)
	s_barrier
	s_setprio 1
	s_waitcnt lgkmcnt(7)
	v_mfma_f32_16x16x32_bf16 v[24:27], v[24:27], v[150:153], 0
	s_waitcnt lgkmcnt(6)
	v_mfma_f32_16x16x32_bf16 v[24:27], v[158:161], v[154:157], v[24:27]
	ds_read_b128 v[150:153], v149
	ds_read_b128 v[154:157], v149 offset:64
	ds_read_b128 v[216:219], v147
	ds_read_b128 v[220:223], v147 offset:64
	ds_read_b128 v[224:227], v147 offset:2304
	ds_read_b128 v[228:231], v147 offset:2368
	s_waitcnt lgkmcnt(7)
	v_mfma_f32_16x16x32_bf16 v[24:27], v[170:173], v[162:165], v[24:27]
	s_waitcnt lgkmcnt(6)
	v_mfma_f32_16x16x32_bf16 v[24:27], v[174:177], v[166:169], v[24:27]
	s_waitcnt lgkmcnt(5)
	v_mfma_f32_16x16x32_bf16 v[24:27], v[190:193], v[150:153], v[24:27]
	s_waitcnt lgkmcnt(4)
	v_mfma_f32_16x16x32_bf16 v[24:27], v[194:197], v[154:157], v[24:27]
	s_and_saveexec_b64 s[24:25], s[6:7]
	s_cbranch_execz .LBB0_150
	s_nop 5
	v_cvt_pk_bf16_f32 v24, v24, s0
	global_store_short v[110:111], v24, off
	s_or_b64 exec, exec, s[24:25]
	s_and_saveexec_b64 s[24:25], s[8:9]
	s_cbranch_execnz .LBB0_151

.LBB0_154:
	s_or_b64 exec, exec, s[24:25]
	s_nop 0
	v_pk_mul_f32 v[26:27], v[112:113], v[74:75] op_sel_hi:[0,1]
	v_pk_mul_f32 v[24:25], v[112:113], v[72:73] op_sel_hi:[0,1]
	s_waitcnt lgkmcnt(3)
	s_nop 0
	v_mfma_f32_16x16x32_bf16 v[24:27], v[80:83], v[216:219], v[24:27]
	s_nop 0
	s_waitcnt lgkmcnt(2)
	v_mfma_f32_16x16x32_bf16 v[24:27], v[36:39], v[220:223], v[24:27]
	v_mul_f32_e64 v152, v112, v78
	v_mul_f32_e64 v153, v112, v79
	s_nop 5
	v_cvt_pk_bf16_f32 v150, v24, v25
	v_cvt_pk_bf16_f32 v151, v26, v27
	ds_write_b64 v87, v[150:151]
	s_nop 0
	v_pk_mul_f32 v[150:151], v[112:113], v[76:77] op_sel_hi:[0,1]
	s_waitcnt lgkmcnt(2)
	s_nop 0
	v_mfma_f32_16x16x32_bf16 v[80:83], v[80:83], v[224:227], v[150:153]
	s_nop 2
	s_nop 0
	s_waitcnt lgkmcnt(1)
	v_mfma_f32_16x16x32_bf16 v[36:39], v[36:39], v[228:231], v[80:83]
	s_nop 7
	v_cvt_pk_bf16_f32 v80, v36, v37
	v_cvt_pk_bf16_f32 v81, v38, v39
	ds_write_b64 v87, v[80:81] offset:4352
	s_setprio 0
	s_waitcnt vmcnt(16)
	ds_write_b128 v115, v[40:43]
	s_waitcnt vmcnt(15)
	ds_write_b128 v116, v[44:47]
	s_waitcnt vmcnt(14)
	ds_write_b128 v115, v[48:51] offset:17408
	s_waitcnt vmcnt(13)
	ds_write_b128 v116, v[52:55] offset:17408
	s_waitcnt vmcnt(12)
	ds_write_b128 v117, v[56:59] offset:34816
	s_waitcnt vmcnt(11)
	ds_write_b128 v118, v[60:63] offset:34816
	s_waitcnt vmcnt(10)
	ds_write_b128 v117, v[64:67] offset:53248
	s_and_saveexec_b64 s[24:25], s[4:5]
	s_cbranch_execz .LBB0_156
	s_waitcnt vmcnt(9)
	ds_write_b128 v117, v[68:71] offset:62464

; __device__ __forceinline__ void attn_phase(unsigned char* lds, const Params& p, int l, const int tid) {
;     ...
;         if (xmap) {
;             const int xcd = blockIdx.x & 7, local = blockIdx.x >> 3; b = xcd;
;             if (local < 8) { smp = (itn == 0); h = smp ? local : itn - 1; cp = local; if (itn > 8) break; }
;             else { smp = false; h = itn; cp = local; if (itn > 7) break; }
.LBB0_367:
	v_readlane_b32 s14, v247, 56
	s_nop 3
	s_cmp_gt_u32 s14, 31
	s_cselect_b64 s[14:15], -1, 0
	s_mov_b64 s[20:21], -1
	s_mov_b64 s[12:13], 0
	s_and_b64 vcc, exec, s[14:15]
	s_mov_b64 s[14:15], 0
	s_cbranch_vccz .LBB0_371
	s_cmp_lt_u32 s49, 8
	s_cselect_b64 s[14:15], -1, 0
	s_mov_b32 s30, s49
	s_cbranch_execz .LBB0_372

; __device__ __forceinline__ void attn_phase(unsigned char* lds, const Params& p, int l, const int tid) {
;     ...
;             const int xcd = blockIdx.x & 7, local = blockIdx.x >> 3; b = xcd;
;             if (local < 8) { smp = (itn == 0); h = smp ? local : itn - 1; cp = local; if (itn > 8) break; }
;             else { smp = false; h = itn; cp = local; if (itn > 7) break; }
.LBB0_372:
	s_cmp_lt_u32 s49, 2
	s_cselect_b64 s[12:13], -1, 0
	s_lshl_b32 s14, s49, 2
	v_readlane_b32 s15, v248, 25
	s_nop 3
	s_add_i32 s15, s15, s14
	s_add_i32 s14, s49, -2
	s_cmp_lt_u32 s49, 2
	s_cselect_b32 s30, s15, s14
	s_cmp_lt_u32 s49, 10
	s_cselect_b64 s[14:15], -1, 0
	s_andn2_b64 vcc, exec, s[14:15]
	s_cbranch_vccz .LBB0_370
